# LayerNorm loop: counted wait vmcnt(4) instead of vmcnt(0) so the row's own stores are not drained mid-iteration (on top of the HGRN priority raise)
# speedup vs baseline: 1.0058x; 1.0026x over previous
; __device__ __forceinline__ u32x2 pack4(f32x4 v) { u32x2 w; w.x = cvt_pk_bf16(v[0], v[1]); w.y = cvt_pk_bf16(v[2], v[3]); return w; }
; __device__ __forceinline__ void phase_ln(const bf16_t* zin, float* xout, bf16_t* xb, float* stats, float* gbtab, const float* __restrict__ g, const float* __restrict__ b) {
;     ...
;         const float rstd = rsqrtf(q * (1.0f / DM) + LN_EPS);
;         if (stats && lane == 0) { stats[2 * row] = mu; stats[2 * row + 1] = rstd; }
; #pragma unroll
;         for (int i = 0; i < 4; ++i) {
;             const int e0 = (lane + 64 * i) * 8;
;             const f32x4 g0 = gh[i][0], g1 = gh[i][1], b0 = bh[i][0], b1 = bh[i][1];
;             const f32x4 y0 = (v[2 * i] - mu) * rstd * g0 + b0, y1 = (v[2 * i + 1] - mu) * rstd * g1 + b1;
;             if (xout) { *(f32x4*)(xout + (size_t)row * DM + e0) = y0; *(f32x4*)(xout + (size_t)row * DM + e0 + 4) = y1; }
;             if (xb) { const u32x2 w0 = pack4(y0), w1 = pack4(y1); u32x4 w; w.x = w0.x; w.y = w0.y; w.z = w1.x; w.w = w1.y; *(u32x4*)(xb + (size_t)row * DM + e0) = w; }
;         }
.LBB0_577:
	v_mov_b32_e32 v84, v114
	v_mov_b32_e32 v85, v114
	v_pk_mul_f32 v[80:81], v[90:91], v[84:85]
	v_pk_mul_f32 v[86:87], v[94:95], v[114:115]
	v_pk_mul_f32 v[84:85], v[88:89], v[84:85]
	v_pk_mul_f32 v[88:89], v[92:93], v[114:115]
	s_waitcnt vmcnt(4)
	v_pk_fma_f32 v[82:83], v[54:55], v[80:81], v[62:63]
	v_pk_fma_f32 v[80:81], v[52:53], v[86:87], v[60:61]
	v_pk_fma_f32 v[86:87], v[50:51], v[84:85], v[58:59]
	s_and_b64 vcc, exec, s[40:41]
	v_pk_fma_f32 v[84:85], v[48:49], v[88:89], v[56:57]
	s_cbranch_vccnz .LBB0_579
	global_store_dwordx4 v[102:103], v[80:83], off offset:2048
	global_store_dwordx4 v[102:103], v[84:87], off offset:2064
